# v84 candidate: v81 + redundant QK s_nop removed + SwiGLU log2e fold + GU leading-half alignment barrier deferred into its epilogue
# speedup vs baseline: 1.0045x; 1.0045x over previous
; __device__ __forceinline__ unsigned cvt_pk_bf16(float lo, float hi) { unsigned r; asm volatile("v_cvt_pk_bf16_f32 %0, %1, %2" : "=v"(r) : "v"(lo), "v"(hi)); return r; }
; __device__ __forceinline__ float silu_mul(float g, float u) { const float e = __builtin_amdgcn_exp2f(g * -1.4426950408889634f); return g * u * __builtin_amdgcn_rcpf(1.0f + e); }
;     __device__ __forceinline__ void operator()(const f32x4 (&acc)[2][2][4][2], const Unit& u, int wr, int wc, int fr, int fq, const PG8_LAS float* rc, bool cached) const {
;     ...
;             for (int m = 0; m < 4; ++m) { const int row = row0 + ai * HALF + m * 16; const float rs = rsv[ai * 4 + m];
;                 const f32x4 g0 = acc[ai][0][m][0] * rs, g1 = acc[ai][0][m][1] * rs, u0 = acc[ai][1][m][0] * rs, u1 = acc[ai][1][m][1] * rs;
;                 u32x4 w; w.x = cvt_pk_bf16(silu_mul(g0[0], u0[0]), silu_mul(g0[1], u0[1])); w.y = cvt_pk_bf16(silu_mul(g0[2], u0[2]), silu_mul(g0[3], u0[3]));
;                 w.z = cvt_pk_bf16(silu_mul(g1[0], u1[0]), silu_mul(g1[1], u1[1])); w.w = cvt_pk_bf16(silu_mul(g1[2], u1[2]), silu_mul(g1[3], u1[3]));
;                 *(u32x4*)(H + (size_t)row * 5632 + col0) = w; }
.LBB0_170:
	s_waitcnt lgkmcnt(0)
	v_mul_f32_e32 v0, 0x3fb8aa3b, v0
	v_mul_f32_e32 v1, 0x3fb8aa3b, v1
	v_mul_f32_e32 v2, 0x3fb8aa3b, v2
	v_mul_f32_e32 v3, 0x3fb8aa3b, v3
	v_mul_f32_e32 v4, 0x3fb8aa3b, v4
	v_mul_f32_e32 v5, 0x3fb8aa3b, v5
	v_mul_f32_e32 v6, 0x3fb8aa3b, v6
	v_mul_f32_e32 v7, 0x3fb8aa3b, v7
	v_mov_b32_e32 v251, 0x40053526
	v_pk_mul_f32 v[132:133], v[132:133], v[0:1] op_sel_hi:[1,0]
	v_pk_mul_f32 v[124:125], v[124:125], v[0:1] op_sel_hi:[1,0]
	v_exp_f32_e64 v140, -v132
	v_mul_f32_e32 v124, v132, v124
	v_mul_f32_e32 v125, v133, v125
	v_pk_mul_f32 v[134:135], v[134:135], v[0:1] op_sel_hi:[1,0]
	v_fma_f32 v132, v140, v251, v251
	v_rcp_f32_e32 v132, v132
	v_pk_mul_f32 v[126:127], v[126:127], v[0:1] op_sel_hi:[1,0]
	v_pk_mul_f32 v[128:129], v[128:129], v[0:1] op_sel_hi:[1,0]
	v_mul_f32_e32 v126, v134, v126
	v_mul_f32_e32 v124, v124, v132
	v_exp_f32_e64 v132, -v133
	v_mul_f32_e32 v127, v135, v127
	v_pk_mul_f32 v[120:121], v[120:121], v[0:1] op_sel_hi:[1,0]
	v_pk_mul_f32 v[130:131], v[130:131], v[0:1] op_sel_hi:[1,0]
	v_fma_f32 v132, v132, v251, v251
	v_rcp_f32_e32 v132, v132
	v_mul_f32_e32 v120, v128, v120
	v_mul_f32_e32 v121, v129, v121
	v_pk_mul_f32 v[122:123], v[122:123], v[0:1] op_sel_hi:[1,0]
	v_mul_f32_e32 v125, v125, v132
	v_cvt_pk_bf16_f32 v124, v124, v125
	v_exp_f32_e64 v125, -v134
	v_lshl_or_b32 v138, s49, 7, v207
	v_add_u32_e32 v138, v138, v209
	v_ashrrev_i32_e32 v139, 31, v138
	v_fma_f32 v125, v125, v251, v251
	v_rcp_f32_e32 v125, v125
	v_pk_mul_f32 v[116:117], v[116:117], v[0:1] op_sel:[0,1]
	v_pk_mul_f32 v[118:119], v[118:119], v[0:1] op_sel:[0,1]
	v_pk_mul_f32 v[114:115], v[114:115], v[0:1] op_sel:[0,1]
	v_mul_f32_e32 v125, v126, v125
	v_exp_f32_e64 v126, -v135
	v_pk_mul_f32 v[112:113], v[112:113], v[0:1] op_sel:[0,1]
	v_pk_mul_f32 v[110:111], v[110:111], v[0:1] op_sel:[0,1]
	v_pk_mul_f32 v[108:109], v[108:109], v[0:1] op_sel:[0,1]
	v_fma_f32 v126, v126, v251, v251
	v_rcp_f32_e32 v126, v126
	v_pk_mul_f32 v[100:101], v[100:101], v[2:3] op_sel_hi:[1,0]
	v_pk_mul_f32 v[98:99], v[98:99], v[2:3] op_sel_hi:[1,0]
	v_pk_mul_f32 v[96:97], v[96:97], v[2:3] op_sel_hi:[1,0]
	v_mul_f32_e32 v126, v127, v126
	v_cvt_pk_bf16_f32 v125, v125, v126
	v_exp_f32_e64 v126, -v128
	v_pk_mul_f32 v[94:95], v[94:95], v[2:3] op_sel_hi:[1,0]
	v_pk_mul_f32 v[92:93], v[92:93], v[2:3] op_sel_hi:[1,0]
	v_pk_mul_f32 v[66:67], v[66:67], v[4:5] op_sel_hi:[1,0]
	v_fma_f32 v126, v126, v251, v251
	v_rcp_f32_e32 v126, v126
	v_pk_mul_f32 v[64:65], v[64:65], v[4:5] op_sel_hi:[1,0]
	v_pk_mul_f32 v[62:63], v[62:63], v[4:5] op_sel_hi:[1,0]
	v_pk_mul_f32 v[60:61], v[60:61], v[4:5] op_sel_hi:[1,0]
	v_mul_f32_e32 v120, v120, v126
	v_exp_f32_e64 v126, -v129
	v_pk_mul_f32 v[58:59], v[58:59], v[4:5] op_sel_hi:[1,0]
	v_pk_mul_f32 v[56:57], v[56:57], v[4:5] op_sel_hi:[1,0]
	v_pk_mul_f32 v[32:33], v[32:33], v[6:7] op_sel_hi:[1,0]
	v_fma_f32 v126, v126, v251, v251
	v_rcp_f32_e32 v126, v126
	v_pk_mul_f32 v[30:31], v[30:31], v[6:7] op_sel_hi:[1,0]
	v_pk_mul_f32 v[28:29], v[28:29], v[6:7] op_sel_hi:[1,0]
	v_pk_mul_f32 v[26:27], v[26:27], v[6:7] op_sel_hi:[1,0]
	v_mul_f32_e32 v121, v121, v126
	v_cvt_pk_bf16_f32 v126, v120, v121
	v_exp_f32_e64 v120, -v130
	v_mul_f32_e32 v121, v130, v122
	v_mul_f32_e32 v122, v131, v123
	v_pk_mul_f32 v[24:25], v[24:25], v[6:7] op_sel_hi:[1,0]
	v_fma_f32 v120, v120, v251, v251
	v_rcp_f32_e32 v120, v120
	s_andn2_b64 vcc, exec, s[4:5]
	v_mul_f32_e32 v120, v121, v120
	v_exp_f32_e64 v121, -v131
	s_nop 0
	v_fma_f32 v121, v121, v251, v251
	v_rcp_f32_e32 v121, v121
	s_nop 0
	v_mul_f32_e32 v121, v122, v121
	v_cvt_pk_bf16_f32 v127, v120, v121
	v_mov_b64_e32 v[120:121], s[16:17]
	v_mad_u64_u32 v[128:129], s[6:7], v200, s57, v[120:121]
	v_mov_b32_e32 v122, v129
	v_mad_u64_u32 v[122:123], s[6:7], v201, s57, v[122:123]
	v_mov_b32_e32 v129, v122
	v_lshlrev_b64 v[122:123], 1, v[138:139]
	v_lshl_add_u64 v[128:129], v[128:129], 0, v[122:123]
	global_store_dwordx4 v[128:129], v[124:127], off
	s_nop 1
	v_pk_mul_f32 v[124:125], v[106:107], v[0:1] op_sel:[0,1]
	v_pk_mul_f32 v[0:1], v[104:105], v[0:1] op_sel:[0,1]
	v_exp_f32_e64 v104, -v116
	v_mul_f32_e32 v105, v116, v108
	v_mul_f32_e32 v106, v117, v109
	v_mul_f32_e32 v107, v119, v111
	v_fma_f32 v104, v104, v251, v251
	v_rcp_f32_e32 v104, v104
	v_mul_f32_e32 v0, v112, v0
	v_mul_f32_e32 v1, v113, v1
	v_mul_f32_e32 v104, v105, v104
	s_cmp_lg_u64 s[20:21], 0
	s_cbranch_scc0 .Lgu_nb
	s_barrier
; __device__ __forceinline__ unsigned cvt_pk_bf16(float lo, float hi) { unsigned r; asm volatile("v_cvt_pk_bf16_f32 %0, %1, %2" : "=v"(r) : "v"(lo), "v"(hi)); return r; }
; __device__ __forceinline__ float silu_mul(float g, float u) { const float e = __builtin_amdgcn_exp2f(g * -1.4426950408889634f); return g * u * __builtin_amdgcn_rcpf(1.0f + e); }
;     __device__ __forceinline__ void operator()(const f32x4 (&acc)[2][2][4][2], const Unit& u, int wr, int wc, int fr, int fq, const PG8_LAS float* rc, bool cached) const {
;     ...
;             for (int m = 0; m < 4; ++m) { const int row = row0 + ai * HALF + m * 16; const float rs = rsv[ai * 4 + m];
;                 const f32x4 g0 = acc[ai][0][m][0] * rs, g1 = acc[ai][0][m][1] * rs, u0 = acc[ai][1][m][0] * rs, u1 = acc[ai][1][m][1] * rs;
;                 u32x4 w; w.x = cvt_pk_bf16(silu_mul(g0[0], u0[0]), silu_mul(g0[1], u0[1])); w.y = cvt_pk_bf16(silu_mul(g0[2], u0[2]), silu_mul(g0[3], u0[3]));
;                 w.z = cvt_pk_bf16(silu_mul(g1[0], u1[0]), silu_mul(g1[1], u1[1])); w.w = cvt_pk_bf16(silu_mul(g1[2], u1[2]), silu_mul(g1[3], u1[3]));
;                 *(u32x4*)(H + (size_t)row * 5632 + col0) = w; }
.Lgu_nb:
	v_exp_f32_e64 v105, -v117
	s_nop 0
	v_fma_f32 v105, v105, v251, v251
	v_rcp_f32_e32 v105, v105
	s_nop 0
	v_mul_f32_e32 v105, v106, v105
	v_cvt_pk_bf16_f32 v104, v104, v105
	v_exp_f32_e64 v105, -v118
	v_mul_f32_e32 v106, v118, v110
	v_fma_f32 v105, v105, v251, v251
	v_rcp_f32_e32 v105, v105
	s_nop 0
	v_mul_f32_e32 v105, v106, v105
	v_exp_f32_e64 v106, -v119
	s_nop 0
	v_fma_f32 v106, v106, v251, v251
	v_rcp_f32_e32 v106, v106
	s_nop 0
	v_mul_f32_e32 v106, v107, v106
	v_cvt_pk_bf16_f32 v105, v105, v106
	v_exp_f32_e64 v106, -v112
	v_mul_f32_e32 v107, v115, v125
	v_fma_f32 v106, v106, v251, v251
	v_rcp_f32_e32 v106, v106
	s_nop 0
	v_mul_f32_e32 v0, v0, v106
	v_exp_f32_e64 v106, -v113
	s_nop 0
	v_fma_f32 v106, v106, v251, v251
	v_rcp_f32_e32 v106, v106
	s_nop 0
	v_mul_f32_e32 v1, v1, v106
	v_cvt_pk_bf16_f32 v106, v0, v1
	v_exp_f32_e64 v0, -v114
	v_mul_f32_e32 v1, v114, v124
	v_fma_f32 v0, v0, v251, v251
	v_rcp_f32_e32 v0, v0
	s_nop 0
	v_mul_f32_e32 v0, v1, v0
	v_exp_f32_e64 v1, -v115
	s_nop 0
	v_fma_f32 v1, v1, v251, v251
	v_rcp_f32_e32 v1, v1
	s_nop 0
	v_mul_f32_e32 v1, v107, v1
	v_cvt_pk_bf16_f32 v107, v0, v1
	v_mad_u64_u32 v[0:1], s[6:7], v198, s57, v[120:121]
	v_mov_b32_e32 v108, v1
	v_mad_u64_u32 v[108:109], s[6:7], v199, s57, v[108:109]
	v_mov_b32_e32 v1, v108
	v_lshl_add_u64 v[0:1], v[0:1], 0, v[122:123]
	global_store_dwordx4 v[0:1], v[104:107], off
	v_pk_mul_f32 v[0:1], v[102:103], v[2:3] op_sel_hi:[1,0]
	v_pk_mul_f32 v[102:103], v[90:91], v[2:3] op_sel_hi:[1,0]
	v_pk_mul_f32 v[90:91], v[88:89], v[2:3] op_sel_hi:[1,0]
	v_exp_f32_e64 v2, -v100
	v_mul_f32_e32 v88, v100, v92
	v_mul_f32_e32 v89, v101, v93
	v_fma_f32 v2, v2, v251, v251
	v_rcp_f32_e32 v2, v2
	s_nop 0
	v_mul_f32_e32 v2, v88, v2
	v_exp_f32_e64 v88, -v101
	s_nop 0
	v_fma_f32 v88, v88, v251, v251
	v_rcp_f32_e32 v88, v88
	s_nop 0
	v_mul_f32_e32 v88, v89, v88
	v_cvt_pk_bf16_f32 v88, v2, v88
	v_exp_f32_e64 v2, -v0
	v_mul_f32_e32 v0, v0, v94
	v_fma_f32 v2, v2, v251, v251
	v_rcp_f32_e32 v2, v2
	s_nop 0
	v_mul_f32_e32 v0, v0, v2
	v_exp_f32_e64 v2, -v1
	v_mul_f32_e32 v1, v1, v95
	v_fma_f32 v2, v2, v251, v251
	v_rcp_f32_e32 v2, v2
	s_nop 0
	v_mul_f32_e32 v1, v1, v2
	v_cvt_pk_bf16_f32 v89, v0, v1
	v_exp_f32_e64 v0, -v96
	v_mul_f32_e32 v1, v96, v90
	v_mul_f32_e32 v2, v97, v91
	v_fma_f32 v0, v0, v251, v251
	v_rcp_f32_e32 v0, v0
	s_nop 0
	v_mul_f32_e32 v0, v1, v0
	v_exp_f32_e64 v1, -v97
	s_nop 0
	v_fma_f32 v1, v1, v251, v251
	v_rcp_f32_e32 v1, v1
	s_nop 0
	v_mul_f32_e32 v1, v2, v1
	v_cvt_pk_bf16_f32 v90, v0, v1
	v_exp_f32_e64 v0, -v98
	v_mul_f32_e32 v1, v98, v102
	v_mul_f32_e32 v2, v99, v103
	v_fma_f32 v0, v0, v251, v251
	v_rcp_f32_e32 v0, v0
	s_nop 0
	v_mul_f32_e32 v0, v1, v0
	v_exp_f32_e64 v1, -v99
	s_nop 0
	v_fma_f32 v1, v1, v251, v251
	v_rcp_f32_e32 v1, v1
	s_nop 0
	v_mul_f32_e32 v1, v2, v1
	v_cvt_pk_bf16_f32 v91, v0, v1
	v_mad_u64_u32 v[0:1], s[6:7], v196, s57, v[120:121]
	v_mov_b32_e32 v2, v1
	v_mad_u64_u32 v[92:93], s[6:7], v197, s57, v[2:3]
	v_mov_b32_e32 v1, v92
	v_lshl_add_u64 v[0:1], v[0:1], 0, v[122:123]
	global_store_dwordx4 v[0:1], v[88:91], off
	v_mov_b32_e32 v0, v3
	v_pk_mul_f32 v[84:85], v[84:85], v[0:1] op_sel_hi:[1,0]
	v_pk_mul_f32 v[2:3], v[86:87], v[0:1] op_sel_hi:[1,0]
	v_pk_mul_f32 v[82:83], v[82:83], v[0:1] op_sel_hi:[1,0]
	v_pk_mul_f32 v[80:81], v[80:81], v[0:1] op_sel_hi:[1,0]
	v_pk_mul_f32 v[78:79], v[78:79], v[0:1] op_sel_hi:[1,0]
	v_pk_mul_f32 v[76:77], v[76:77], v[0:1] op_sel_hi:[1,0]
	v_pk_mul_f32 v[74:75], v[74:75], v[0:1] op_sel_hi:[1,0]
	v_pk_mul_f32 v[72:73], v[72:73], v[0:1] op_sel_hi:[1,0]
	v_exp_f32_e64 v0, -v84
	v_mul_f32_e32 v1, v84, v76
	v_mul_f32_e32 v76, v85, v77
	v_fma_f32 v0, v0, v251, v251
	v_rcp_f32_e32 v0, v0
	s_nop 0
	v_mul_f32_e32 v0, v1, v0
	v_exp_f32_e64 v1, -v85
	s_nop 0
	v_fma_f32 v1, v1, v251, v251
	v_rcp_f32_e32 v1, v1
	s_nop 0
	v_mul_f32_e32 v1, v76, v1
	v_cvt_pk_bf16_f32 v0, v0, v1
	v_exp_f32_e64 v1, -v2
	v_mul_f32_e32 v2, v2, v78
	v_fma_f32 v1, v1, v251, v251
	v_rcp_f32_e32 v1, v1
	s_nop 0
	v_mul_f32_e32 v1, v2, v1
	v_exp_f32_e64 v2, -v3
	v_mul_f32_e32 v3, v3, v79
	v_fma_f32 v2, v2, v251, v251
	v_rcp_f32_e32 v2, v2
	s_nop 0
	v_mul_f32_e32 v2, v3, v2
	v_cvt_pk_bf16_f32 v1, v1, v2
	v_exp_f32_e64 v2, -v80
	v_mul_f32_e32 v3, v80, v72
	v_mul_f32_e32 v72, v81, v73
	v_mul_f32_e32 v73, v83, v75
	v_fma_f32 v2, v2, v251, v251
	v_rcp_f32_e32 v2, v2
	s_nop 0
	v_mul_f32_e32 v2, v3, v2
	v_exp_f32_e64 v3, -v81
	s_nop 0
	v_fma_f32 v3, v3, v251, v251
	v_rcp_f32_e32 v3, v3
	s_nop 0
	v_mul_f32_e32 v3, v72, v3
	v_cvt_pk_bf16_f32 v2, v2, v3
	v_exp_f32_e64 v3, -v82
	v_mul_f32_e32 v72, v82, v74
	v_fma_f32 v3, v3, v251, v251
	v_rcp_f32_e32 v3, v3
	s_nop 0
	v_mul_f32_e32 v3, v72, v3
	v_exp_f32_e64 v72, -v83
	s_nop 0
	v_fma_f32 v72, v72, v251, v251
	v_rcp_f32_e32 v72, v72
	s_nop 0
	v_mul_f32_e32 v72, v73, v72
	v_cvt_pk_bf16_f32 v3, v3, v72
	v_mad_u64_u32 v[72:73], s[6:7], v194, s57, v[120:121]
	v_mov_b32_e32 v74, v73
	v_mad_u64_u32 v[74:75], s[6:7], v195, s57, v[74:75]
	v_mov_b32_e32 v73, v74
	v_lshl_add_u64 v[72:73], v[72:73], 0, v[122:123]
	global_store_dwordx4 v[72:73], v[0:3], off
	s_nop 1
	v_pk_mul_f32 v[0:1], v[68:69], v[4:5] op_sel_hi:[1,0]
	v_pk_mul_f32 v[2:3], v[70:71], v[4:5] op_sel_hi:[1,0]
	v_exp_f32_e64 v4, -v0
	v_mul_f32_e32 v0, v0, v60
	v_fma_f32 v4, v4, v251, v251
	v_rcp_f32_e32 v4, v4
	s_nop 0
	v_mul_f32_e32 v0, v0, v4
	v_exp_f32_e64 v4, -v1
	v_mul_f32_e32 v1, v1, v61
	v_fma_f32 v4, v4, v251, v251
	v_rcp_f32_e32 v4, v4
	s_nop 0
	v_mul_f32_e32 v1, v1, v4
	v_cvt_pk_bf16_f32 v0, v0, v1
	v_exp_f32_e64 v1, -v2
	v_mul_f32_e32 v2, v2, v62
	v_mul_f32_e32 v4, v65, v57
	v_fma_f32 v1, v1, v251, v251
	v_rcp_f32_e32 v1, v1
	s_nop 0
; #define PG8_LAS __attribute__((address_space(3)))
; __device__ __forceinline__ unsigned cvt_pk_bf16(float lo, float hi) { unsigned r; asm volatile("v_cvt_pk_bf16_f32 %0, %1, %2" : "=v"(r) : "v"(lo), "v"(hi)); return r; }
; __device__ __forceinline__ float silu_mul(float g, float u) { const float e = __builtin_amdgcn_exp2f(g * -1.4426950408889634f); return g * u * __builtin_amdgcn_rcpf(1.0f + e); }
; #define PG8_BAR __builtin_amdgcn_s_barrier()
;     __device__ __forceinline__ void operator()(const f32x4 (&acc)[2][2][4][2], const Unit& u, int wr, int wc, int fr, int fq, const PG8_LAS float* rc, bool cached) const {
;     ...
;             for (int m = 0; m < 4; ++m) { const int row = row0 + ai * HALF + m * 16; const float rs = rsv[ai * 4 + m];
;                 const f32x4 g0 = acc[ai][0][m][0] * rs, g1 = acc[ai][0][m][1] * rs, u0 = acc[ai][1][m][0] * rs, u1 = acc[ai][1][m][1] * rs;
;                 u32x4 w; w.x = cvt_pk_bf16(silu_mul(g0[0], u0[0]), silu_mul(g0[1], u0[1])); w.y = cvt_pk_bf16(silu_mul(g0[2], u0[2]), silu_mul(g0[3], u0[3]));
;                 w.z = cvt_pk_bf16(silu_mul(g1[0], u1[0]), silu_mul(g1[1], u1[1])); w.w = cvt_pk_bf16(silu_mul(g1[2], u1[2]), silu_mul(g1[3], u1[3]));
;                 *(u32x4*)(H + (size_t)row * 5632 + col0) = w; }
; template <class Epi, class Sched, bool ALIGN_EPI = false, bool SP2 = false, bool HALFM = false, bool AMAP = false>
; __device__ __forceinline__ void gemm_phase(PG8_LAS unsigned char* lds, const Gemm g, const Sched& S, const Epi& E, int tid_in) {
;     ...
;         if constexpr (!Epi::AFTER_DRAIN) { if constexpr (Epi::RSTD) E(acc, cur, wr, wc, fr, fq, (const PG8_LAS float*)(lds + STAGE_BYTES), cur.pm == pm0); else E(acc, cur, wr, wc, fr, fq); S.done(cur); }
;         if (!has_next) break;
; #pragma unroll
;         for (int a = 0; a < 2; ++a)
; #pragma unroll
;             for (int b = 0; b < 2; ++b)
; #pragma unroll
;                 for (int m = 0; m < 4; ++m)
; #pragma unroll
;                     for (int n = 0; n < 2; ++n) acc[a][b][m][n] = (f32x4){0.f, 0.f, 0.f, 0.f};
;         cur = nxt; cA = nA; cB = nB; ++ui;
;         if constexpr (ALIGN_EPI) { if (wr == 1) PG8_BAR; }
	v_mul_f32_e32 v1, v2, v1
	v_exp_f32_e64 v2, -v3
	v_mul_f32_e32 v3, v3, v63
	v_fma_f32 v2, v2, v251, v251
	v_rcp_f32_e32 v2, v2
	s_nop 0
	v_mul_f32_e32 v2, v3, v2
	v_cvt_pk_bf16_f32 v1, v1, v2
	v_exp_f32_e64 v2, -v64
	v_mul_f32_e32 v3, v64, v56
	v_mul_f32_e32 v56, v67, v59
	v_fma_f32 v2, v2, v251, v251
	v_rcp_f32_e32 v2, v2
	s_nop 0
	v_mul_f32_e32 v2, v3, v2
	v_exp_f32_e64 v3, -v65
	s_nop 0
	v_fma_f32 v3, v3, v251, v251
	v_rcp_f32_e32 v3, v3
	s_nop 0
	v_mul_f32_e32 v3, v4, v3
	v_cvt_pk_bf16_f32 v2, v2, v3
	v_exp_f32_e64 v3, -v66
	v_mul_f32_e32 v4, v66, v58
	v_fma_f32 v3, v3, v251, v251
	v_rcp_f32_e32 v3, v3
	s_nop 0
	v_mul_f32_e32 v3, v4, v3
	v_exp_f32_e64 v4, -v67
	s_nop 0
	v_fma_f32 v4, v4, v251, v251
	v_rcp_f32_e32 v4, v4
	s_nop 0
	v_mul_f32_e32 v4, v56, v4
	v_mad_u64_u32 v[56:57], s[6:7], v136, s57, v[120:121]
	v_cvt_pk_bf16_f32 v3, v3, v4
	v_mov_b32_e32 v4, v57
	v_mad_u64_u32 v[58:59], s[6:7], v137, s57, v[4:5]
	v_mov_b32_e32 v57, v58
	v_lshl_add_u64 v[56:57], v[56:57], 0, v[122:123]
	global_store_dwordx4 v[56:57], v[0:3], off
	v_add_u32_e32 v56, 16, v192
	s_nop 0
	v_mov_b32_e32 v0, v5
	v_pk_mul_f32 v[4:5], v[52:53], v[0:1] op_sel_hi:[1,0]
	v_pk_mul_f32 v[2:3], v[54:55], v[0:1] op_sel_hi:[1,0]
	v_pk_mul_f32 v[50:51], v[50:51], v[0:1] op_sel_hi:[1,0]
	v_pk_mul_f32 v[48:49], v[48:49], v[0:1] op_sel_hi:[1,0]
	v_pk_mul_f32 v[46:47], v[46:47], v[0:1] op_sel_hi:[1,0]
	v_pk_mul_f32 v[44:45], v[44:45], v[0:1] op_sel_hi:[1,0]
	v_pk_mul_f32 v[42:43], v[42:43], v[0:1] op_sel_hi:[1,0]
	v_pk_mul_f32 v[40:41], v[40:41], v[0:1] op_sel_hi:[1,0]
	v_exp_f32_e64 v0, -v4
	v_mul_f32_e32 v1, v4, v44
	v_mul_f32_e32 v4, v5, v45
	v_fma_f32 v0, v0, v251, v251
	v_rcp_f32_e32 v0, v0
	s_nop 0
	v_mul_f32_e32 v0, v1, v0
	v_exp_f32_e64 v1, -v5
	v_mul_f32_e32 v5, v51, v43
	v_fma_f32 v1, v1, v251, v251
	v_rcp_f32_e32 v1, v1
	s_nop 0
	v_mul_f32_e32 v1, v4, v1
	v_cvt_pk_bf16_f32 v0, v0, v1
	v_exp_f32_e64 v1, -v2
	v_mul_f32_e32 v2, v2, v46
	v_mul_f32_e32 v4, v49, v41
	v_fma_f32 v1, v1, v251, v251
	v_rcp_f32_e32 v1, v1
	s_nop 0
	v_mul_f32_e32 v1, v2, v1
	v_exp_f32_e64 v2, -v3
	v_mul_f32_e32 v3, v3, v47
	v_fma_f32 v2, v2, v251, v251
	v_rcp_f32_e32 v2, v2
	s_nop 0
	v_mul_f32_e32 v2, v3, v2
	v_cvt_pk_bf16_f32 v1, v1, v2
	v_exp_f32_e64 v2, -v48
	v_mul_f32_e32 v3, v48, v40
	v_add_u32_e32 v40, 32, v192
	v_fma_f32 v2, v2, v251, v251
	v_rcp_f32_e32 v2, v2
	s_nop 0
	v_mul_f32_e32 v2, v3, v2
	v_exp_f32_e64 v3, -v49
	s_nop 0
	v_fma_f32 v3, v3, v251, v251
	v_rcp_f32_e32 v3, v3
	s_nop 0
	v_mul_f32_e32 v3, v4, v3
	v_cvt_pk_bf16_f32 v2, v2, v3
	v_exp_f32_e64 v3, -v50
	v_mul_f32_e32 v4, v50, v42
	v_fma_f32 v3, v3, v251, v251
	v_rcp_f32_e32 v3, v3
	s_nop 0
	v_mul_f32_e32 v3, v4, v3
	v_exp_f32_e64 v4, -v51
	s_nop 0
	v_fma_f32 v4, v4, v251, v251
	v_rcp_f32_e32 v4, v4
	s_nop 0
	v_mul_f32_e32 v4, v5, v4
	v_cvt_pk_bf16_f32 v3, v3, v4
	v_mad_i64_i32 v[4:5], s[6:7], v56, s57, v[120:121]
	v_lshl_add_u64 v[4:5], v[4:5], 0, v[122:123]
	global_store_dwordx4 v[4:5], v[0:3], off
	v_pk_mul_f32 v[4:5], v[34:35], v[6:7] op_sel_hi:[1,0]
	s_nop 0
	v_pk_mul_f32 v[0:1], v[36:37], v[6:7] op_sel_hi:[1,0]
	v_pk_mul_f32 v[2:3], v[38:39], v[6:7] op_sel_hi:[1,0]
	v_exp_f32_e64 v6, -v0
	v_mul_f32_e32 v0, v0, v28
	v_fma_f32 v6, v6, v251, v251
	v_rcp_f32_e32 v6, v6
	s_nop 0
	v_mul_f32_e32 v0, v0, v6
	v_exp_f32_e64 v6, -v1
	v_mul_f32_e32 v1, v1, v29
	v_fma_f32 v6, v6, v251, v251
	v_rcp_f32_e32 v6, v6
	s_nop 0
	v_mul_f32_e32 v1, v1, v6
	v_cvt_pk_bf16_f32 v0, v0, v1
	v_exp_f32_e64 v1, -v2
	v_mul_f32_e32 v2, v2, v30
	v_mul_f32_e32 v6, v33, v25
	v_fma_f32 v1, v1, v251, v251
	v_rcp_f32_e32 v1, v1
	s_nop 0
	v_mul_f32_e32 v1, v2, v1
	v_exp_f32_e64 v2, -v3
	v_mul_f32_e32 v3, v3, v31
	v_fma_f32 v2, v2, v251, v251
	v_rcp_f32_e32 v2, v2
	s_nop 0
	v_mul_f32_e32 v2, v3, v2
	v_cvt_pk_bf16_f32 v1, v1, v2
	v_exp_f32_e64 v2, -v32
	v_mul_f32_e32 v3, v32, v24
	v_add_u32_e32 v24, 48, v192
	v_fma_f32 v2, v2, v251, v251
	v_rcp_f32_e32 v2, v2
	s_nop 0
	v_mul_f32_e32 v2, v3, v2
	v_exp_f32_e64 v3, -v33
	s_nop 0
	v_fma_f32 v3, v3, v251, v251
	v_rcp_f32_e32 v3, v3
	s_nop 0
	v_mul_f32_e32 v3, v6, v3
	v_cvt_pk_bf16_f32 v2, v2, v3
	v_exp_f32_e64 v3, -v4
	v_mul_f32_e32 v4, v4, v26
	v_fma_f32 v3, v3, v251, v251
	v_rcp_f32_e32 v3, v3
	s_nop 0
	v_mul_f32_e32 v3, v4, v3
	v_exp_f32_e64 v4, -v5
	v_mul_f32_e32 v5, v5, v27
	v_fma_f32 v4, v4, v251, v251
	v_rcp_f32_e32 v4, v4
	s_nop 0
	v_mul_f32_e32 v4, v5, v4
	v_cvt_pk_bf16_f32 v3, v3, v4
	v_mad_i64_i32 v[4:5], s[6:7], v40, s57, v[120:121]
	v_lshl_add_u64 v[4:5], v[4:5], 0, v[122:123]
	global_store_dwordx4 v[4:5], v[0:3], off
	s_nop 1
	v_mov_b32_e32 v0, v7
	v_pk_mul_f32 v[4:5], v[20:21], v[0:1] op_sel_hi:[1,0]
	v_pk_mul_f32 v[2:3], v[22:23], v[0:1] op_sel_hi:[1,0]
	v_pk_mul_f32 v[6:7], v[18:19], v[0:1] op_sel_hi:[1,0]
	v_pk_mul_f32 v[16:17], v[16:17], v[0:1] op_sel_hi:[1,0]
	v_pk_mul_f32 v[14:15], v[14:15], v[0:1] op_sel_hi:[1,0]
	v_pk_mul_f32 v[12:13], v[12:13], v[0:1] op_sel_hi:[1,0]
	v_pk_mul_f32 v[10:11], v[10:11], v[0:1] op_sel_hi:[1,0]
	v_pk_mul_f32 v[8:9], v[8:9], v[0:1] op_sel_hi:[1,0]
	v_exp_f32_e64 v0, -v4
	v_mul_f32_e32 v1, v4, v12
	v_mul_f32_e32 v4, v5, v13
	v_fma_f32 v0, v0, v251, v251
	v_rcp_f32_e32 v0, v0
	s_nop 0
	v_mul_f32_e32 v0, v1, v0
	v_exp_f32_e64 v1, -v5
	v_mul_f32_e32 v5, v7, v11
	v_fma_f32 v1, v1, v251, v251
	v_rcp_f32_e32 v1, v1
	s_nop 0
	v_mul_f32_e32 v1, v4, v1
	v_cvt_pk_bf16_f32 v0, v0, v1
	v_exp_f32_e64 v1, -v2
	v_mul_f32_e32 v2, v2, v14
	v_mul_f32_e32 v4, v17, v9
	v_fma_f32 v1, v1, v251, v251
	v_rcp_f32_e32 v1, v1
	s_nop 0
	v_mul_f32_e32 v1, v2, v1
	v_exp_f32_e64 v2, -v3
	v_mul_f32_e32 v3, v3, v15
	v_fma_f32 v2, v2, v251, v251
	v_rcp_f32_e32 v2, v2
	s_nop 0
	v_mul_f32_e32 v2, v3, v2
	v_cvt_pk_bf16_f32 v1, v1, v2
	v_exp_f32_e64 v2, -v16
	v_mul_f32_e32 v3, v16, v8
	v_fma_f32 v2, v2, v251, v251
	v_rcp_f32_e32 v2, v2
	s_nop 0
	v_mul_f32_e32 v2, v3, v2
	v_exp_f32_e64 v3, -v17
	s_nop 0
	v_fma_f32 v3, v3, v251, v251
	v_rcp_f32_e32 v3, v3
	s_nop 0
	v_mul_f32_e32 v3, v4, v3
	v_cvt_pk_bf16_f32 v2, v2, v3
	v_exp_f32_e64 v3, -v6
	v_mul_f32_e32 v4, v6, v10
	v_fma_f32 v3, v3, v251, v251
	v_rcp_f32_e32 v3, v3
	s_nop 0
	v_mul_f32_e32 v3, v4, v3
	v_exp_f32_e64 v4, -v7
	s_nop 0
	v_fma_f32 v4, v4, v251, v251
	v_rcp_f32_e32 v4, v4
	s_nop 0
	v_mul_f32_e32 v4, v5, v4
	v_cvt_pk_bf16_f32 v3, v3, v4
	v_mad_i64_i32 v[4:5], s[6:7], v24, s57, v[120:121]
	v_lshl_add_u64 v[4:5], v[4:5], 0, v[122:123]
	s_mov_b64 s[6:7], -1
	global_store_dwordx4 v[4:5], v[0:3], off
	s_cbranch_vccnz .LBB0_159
	s_andn2_b64 vcc, exec, s[14:15]
	s_cbranch_vccnz .LBB0_158
	s_barrier
	s_branch .LBB0_158
